# rw_task<2>: row-packed state pairs (row0,row1 per k) so dot products accumulate (sa0,sa1)/(x0,x1) directly, no lo+hi adds
# speedup vs baseline: 1.0122x; 1.0014x over previous
; #define LAS __attribute__((address_space(3)))
; template <int R>
; __device__ __forceinline__ void rw_task(const Params& p, LAS unsigned char* shm, const int tid, const int s, const int d, const int h, const int half) {
;     ...
;                 for (int st = 0; st < TT; ++st) {
;                     const LAS float* sb = ib + st * RW_STRIDE;
;                     f32x2 ww[4], kk[4], bb[4], kc[4], wr[4];
;                     { const f32x4 a = *(const LAS f32x4*)(sb + 8 * j), b = *(const LAS f32x4*)(sb + 8 * j + 4); ww[0] = (f32x2){a[0], a[1]}; ww[1] = (f32x2){a[2], a[3]}; ww[2] = (f32x2){b[0], b[1]}; ww[3] = (f32x2){b[2], b[3]}; }
;                     { const f32x4 a = *(const LAS f32x4*)(sb + 64 + 8 * j), b = *(const LAS f32x4*)(sb + 64 + 8 * j + 4); kk[0] = (f32x2){a[0], a[1]}; kk[1] = (f32x2){a[2], a[3]}; kk[2] = (f32x2){b[0], b[1]}; kk[3] = (f32x2){b[2], b[3]}; }
;                     { const f32x4 a = *(const LAS f32x4*)(sb + 128 + 8 * j), b = *(const LAS f32x4*)(sb + 128 + 8 * j + 4); bb[0] = (f32x2){a[0], a[1]}; bb[1] = (f32x2){a[2], a[3]}; bb[2] = (f32x2){b[0], b[1]}; bb[3] = (f32x2){b[2], b[3]}; }
;                     { const f32x4 a = *(const LAS f32x4*)(sb + 192 + 8 * j), b = *(const LAS f32x4*)(sb + 192 + 8 * j + 4); kc[0] = (f32x2){a[0], a[1]}; kc[1] = (f32x2){a[2], a[3]}; kc[2] = (f32x2){b[0], b[1]}; kc[3] = (f32x2){b[2], b[3]}; }
;                     { const f32x4 a = *(const LAS f32x4*)(sb + 256 + 8 * j), b = *(const LAS f32x4*)(sb + 256 + 8 * j + 4); wr[0] = (f32x2){a[0], a[1]}; wr[1] = (f32x2){a[2], a[3]}; wr[2] = (f32x2){b[0], b[1]}; wr[3] = (f32x2){b[2], b[3]}; }
;                     const float v0 = sb[320 + row0], v1 = R == 2 ? sb[320 + row1] : 0.f; const f32x2 sc = *(const LAS f32x2*)(sb + 384); const float br = sc[0], kr = sc[1];
;                     if constexpr (R == 2) {
;                     f32x2 pa0 = s0[0] * kk[0], px0 = s0[0] * wr[0], pa1 = s1[0] * kk[0], px1 = s1[0] * wr[0];
; #pragma unroll
;                     for (int e = 1; e < 4; ++e) { pa0 += s0[e] * kk[e]; px0 += s0[e] * wr[e]; pa1 += s1[e] * kk[e]; px1 += s1[e] * wr[e]; }
;                     const float sa0 = red8(pa0[0] + pa0[1]), x0 = red8(px0[0] + px0[1]), sa1 = red8(pa1[0] + pa1[1]), x1 = red8(px1[0] + px1[1]);
;                     const float o0 = x0 - sa0 * br + v0 * kr, o1 = x1 - sa1 * br + v1 * kr;
.Lrw2_step:
	ds_read_b128 v[74:77], v130 offset:1552
	ds_read_b128 v[78:81], v130 offset:1568
	ds_read_b128 v[82:85], v130 offset:1808
	ds_read_b128 v[86:89], v130 offset:1824
	ds_read_b128 v[92:95], v130 offset:2064
	ds_read_b128 v[96:99], v130 offset:2080
	ds_read_b128 v[100:103], v130 offset:2320
	ds_read_b128 v[104:107], v130 offset:2336
	ds_read_b128 v[108:111], v130 offset:2576
	ds_read_b128 v[112:115], v130 offset:2592
	ds_read_b32 v116, v132 offset:1552
	ds_read_b32 v117, v132 offset:1584
	ds_read_b64 v[118:119], v133 offset:3088
	s_waitcnt lgkmcnt(13)
	v_pk_mul_f32 v[160:161], v[2:3], v[36:37] op_sel:[0,0] op_sel_hi:[1,0]
	v_pk_mul_f32 v[162:163], v[2:3], v[60:61] op_sel:[0,0] op_sel_hi:[1,0]
	v_pk_fma_f32 v[160:161], v[4:5], v[36:37], v[160:161] op_sel:[0,1,0] op_sel_hi:[1,1,1]
	v_pk_fma_f32 v[162:163], v[4:5], v[60:61], v[162:163] op_sel:[0,1,0] op_sel_hi:[1,1,1]
	v_pk_fma_f32 v[160:161], v[6:7], v[38:39], v[160:161] op_sel:[0,0,0] op_sel_hi:[1,0,1]
	v_pk_fma_f32 v[162:163], v[6:7], v[62:63], v[162:163] op_sel:[0,0,0] op_sel_hi:[1,0,1]
	v_pk_fma_f32 v[160:161], v[8:9], v[38:39], v[160:161] op_sel:[0,1,0] op_sel_hi:[1,1,1]
	v_pk_fma_f32 v[162:163], v[8:9], v[62:63], v[162:163] op_sel:[0,1,0] op_sel_hi:[1,1,1]
	v_pk_fma_f32 v[160:161], v[10:11], v[40:41], v[160:161] op_sel:[0,0,0] op_sel_hi:[1,0,1]
	v_pk_fma_f32 v[162:163], v[10:11], v[64:65], v[162:163] op_sel:[0,0,0] op_sel_hi:[1,0,1]
	v_pk_fma_f32 v[160:161], v[12:13], v[40:41], v[160:161] op_sel:[0,1,0] op_sel_hi:[1,1,1]
	v_pk_fma_f32 v[162:163], v[12:13], v[64:65], v[162:163] op_sel:[0,1,0] op_sel_hi:[1,1,1]
	v_pk_fma_f32 v[160:161], v[14:15], v[42:43], v[160:161] op_sel:[0,0,0] op_sel_hi:[1,0,1]
	v_pk_fma_f32 v[162:163], v[14:15], v[66:67], v[162:163] op_sel:[0,0,0] op_sel_hi:[1,0,1]
	v_pk_fma_f32 v[160:161], v[16:17], v[42:43], v[160:161] op_sel:[0,1,0] op_sel_hi:[1,1,1]
	v_pk_fma_f32 v[162:163], v[16:17], v[66:67], v[162:163] op_sel:[0,1,0] op_sel_hi:[1,1,1]
	v_pk_mul_f32 v[136:137], v[2:3], v[28:29] op_sel:[0,0] op_sel_hi:[1,0]
	v_pk_mul_f32 v[138:139], v[4:5], v[28:29] op_sel:[0,1] op_sel_hi:[1,1]
	v_add_f32_dpp v160, v160, v160 quad_perm:[1,0,3,2] row_mask:0xf bank_mask:0xf bound_ctrl:1
	v_add_f32_dpp v161, v161, v161 quad_perm:[1,0,3,2] row_mask:0xf bank_mask:0xf bound_ctrl:1
	v_pk_mul_f32 v[140:141], v[6:7], v[30:31] op_sel:[0,0] op_sel_hi:[1,0]
	v_pk_mul_f32 v[142:143], v[8:9], v[30:31] op_sel:[0,1] op_sel_hi:[1,1]
	v_add_f32_dpp v162, v162, v162 quad_perm:[1,0,3,2] row_mask:0xf bank_mask:0xf bound_ctrl:1
	v_add_f32_dpp v163, v163, v163 quad_perm:[1,0,3,2] row_mask:0xf bank_mask:0xf bound_ctrl:1
	v_pk_mul_f32 v[148:149], v[10:11], v[32:33] op_sel:[0,0] op_sel_hi:[1,0]
	v_pk_mul_f32 v[150:151], v[12:13], v[32:33] op_sel:[0,1] op_sel_hi:[1,1]
	v_add_f32_dpp v160, v160, v160 quad_perm:[2,3,0,1] row_mask:0xf bank_mask:0xf bound_ctrl:1
	v_add_f32_dpp v161, v161, v161 quad_perm:[2,3,0,1] row_mask:0xf bank_mask:0xf bound_ctrl:1
	v_pk_mul_f32 v[152:153], v[14:15], v[34:35] op_sel:[0,0] op_sel_hi:[1,0]
	v_pk_mul_f32 v[154:155], v[16:17], v[34:35] op_sel:[0,1] op_sel_hi:[1,1]
	v_add_f32_dpp v162, v162, v162 quad_perm:[2,3,0,1] row_mask:0xf bank_mask:0xf bound_ctrl:1
	v_add_f32_dpp v163, v163, v163 quad_perm:[2,3,0,1] row_mask:0xf bank_mask:0xf bound_ctrl:1
	v_pk_fma_f32 v[136:137], v[52:53], v[68:69], v[136:137] op_sel:[0,0,0] op_sel_hi:[0,1,1]
	v_pk_fma_f32 v[138:139], v[52:53], v[68:69], v[138:139] op_sel:[1,0,0] op_sel_hi:[1,1,1]
	v_add_f32_dpp v160, v160, v160 row_half_mirror row_mask:0xf bank_mask:0xf bound_ctrl:1
	v_add_f32_dpp v161, v161, v161 row_half_mirror row_mask:0xf bank_mask:0xf bound_ctrl:1
	v_pk_fma_f32 v[140:141], v[54:55], v[68:69], v[140:141] op_sel:[0,0,0] op_sel_hi:[0,1,1]
	v_pk_fma_f32 v[142:143], v[54:55], v[68:69], v[142:143] op_sel:[1,0,0] op_sel_hi:[1,1,1]
	v_add_f32_dpp v162, v162, v162 row_half_mirror row_mask:0xf bank_mask:0xf bound_ctrl:1
	v_add_f32_dpp v163, v163, v163 row_half_mirror row_mask:0xf bank_mask:0xf bound_ctrl:1
	v_pk_fma_f32 v[148:149], v[56:57], v[68:69], v[148:149] op_sel:[0,0,0] op_sel_hi:[0,1,1]
	v_pk_fma_f32 v[150:151], v[56:57], v[68:69], v[150:151] op_sel:[1,0,0] op_sel_hi:[1,1,1]
	v_pk_fma_f32 v[152:153], v[58:59], v[68:69], v[152:153] op_sel:[0,0,0] op_sel_hi:[0,1,1]
	v_pk_fma_f32 v[154:155], v[58:59], v[68:69], v[154:155] op_sel:[1,0,0] op_sel_hi:[1,1,1]
	v_pk_mul_f32 v[144:145], v[68:69], v[70:71] op_sel:[0,1] op_sel_hi:[1,1]
	v_pk_fma_f32 v[2:3], v[44:45], v[160:161], v[136:137] op_sel:[0,0,0] op_sel_hi:[0,1,1] neg_lo:[0,1,0] neg_hi:[0,1,0]
	v_pk_fma_f32 v[144:145], v[160:161], v[70:71], v[144:145] op_sel_hi:[1,0,1] neg_lo:[1,0,0] neg_hi:[1,0,0]
	v_pk_fma_f32 v[4:5], v[44:45], v[160:161], v[138:139] op_sel:[1,0,0] op_sel_hi:[1,1,1] neg_lo:[0,1,0] neg_hi:[0,1,0]
	v_pk_fma_f32 v[6:7], v[46:47], v[160:161], v[140:141] op_sel:[0,0,0] op_sel_hi:[0,1,1] neg_lo:[0,1,0] neg_hi:[0,1,0]
	v_pk_add_f32 v[128:129], v[162:163], v[144:145]
	v_pk_fma_f32 v[8:9], v[46:47], v[160:161], v[142:143] op_sel:[1,0,0] op_sel_hi:[1,1,1] neg_lo:[0,1,0] neg_hi:[0,1,0]
	v_pk_fma_f32 v[10:11], v[48:49], v[160:161], v[148:149] op_sel:[0,0,0] op_sel_hi:[0,1,1] neg_lo:[0,1,0] neg_hi:[0,1,0]
	v_pk_fma_f32 v[12:13], v[48:49], v[160:161], v[150:151] op_sel:[1,0,0] op_sel_hi:[1,1,1] neg_lo:[0,1,0] neg_hi:[0,1,0]
	v_pk_fma_f32 v[14:15], v[50:51], v[160:161], v[152:153] op_sel:[0,0,0] op_sel_hi:[0,1,1] neg_lo:[0,1,0] neg_hi:[0,1,0]
	v_pk_fma_f32 v[16:17], v[50:51], v[160:161], v[154:155] op_sel:[1,0,0] op_sel_hi:[1,1,1] neg_lo:[0,1,0] neg_hi:[0,1,0]
	ds_write2_b32 v156, v128, v129 offset0:0 offset1:8
	ds_read_b128 v[28:31], v130 offset:3104
	ds_read_b128 v[32:35], v130 offset:3120
	ds_read_b128 v[36:39], v130 offset:3360
	ds_read_b128 v[40:43], v130 offset:3376
	ds_read_b128 v[44:47], v130 offset:3616
	ds_read_b128 v[48:51], v130 offset:3632
	ds_read_b128 v[52:55], v130 offset:3872
	ds_read_b128 v[56:59], v130 offset:3888
	ds_read_b128 v[60:63], v130 offset:4128
	ds_read_b128 v[64:67], v130 offset:4144
	ds_read_b32 v68, v132 offset:3104
	ds_read_b32 v69, v132 offset:3136
	ds_read_b64 v[70:71], v133 offset:4640
	s_waitcnt lgkmcnt(13)
; #define LAS __attribute__((address_space(3)))
; template <int R>
; __device__ __forceinline__ void rw_task(const Params& p, LAS unsigned char* shm, const int tid, const int s, const int d, const int h, const int half) {
;     ...
;                     const float v0 = sb[320 + row0], v1 = R == 2 ? sb[320 + row1] : 0.f; const f32x2 sc = *(const LAS f32x2*)(sb + 384); const float br = sc[0], kr = sc[1];
;                     if constexpr (R == 2) {
;                     f32x2 pa0 = s0[0] * kk[0], px0 = s0[0] * wr[0], pa1 = s1[0] * kk[0], px1 = s1[0] * wr[0];
; #pragma unroll
;                     for (int e = 1; e < 4; ++e) { pa0 += s0[e] * kk[e]; px0 += s0[e] * wr[e]; pa1 += s1[e] * kk[e]; px1 += s1[e] * wr[e]; }
;                     const float sa0 = red8(pa0[0] + pa0[1]), x0 = red8(px0[0] + px0[1]), sa1 = red8(pa1[0] + pa1[1]), x1 = red8(px1[0] + px1[1]);
;                     const float o0 = x0 - sa0 * br + v0 * kr, o1 = x1 - sa1 * br + v1 * kr;
;                     const f32x2 nsa0 = (f32x2){-sa0, -sa0}, nsa1 = (f32x2){-sa1, -sa1}, vv0 = (f32x2){v0, v0}, vv1 = (f32x2){v1, v1};
; #pragma unroll
;                     for (int e = 0; e < 4; ++e) { s0[e] = s0[e] * ww[e] + nsa0 * bb[e] + vv0 * kc[e]; s1[e] = s1[e] * ww[e] + nsa1 * bb[e] + vv1 * kc[e]; }
;                     ow0[(st * 64) & omask] = o0; ow1[(st * 64) & omask] = o1;
	v_pk_mul_f32 v[160:161], v[2:3], v[82:83] op_sel:[0,0] op_sel_hi:[1,0]
	v_pk_mul_f32 v[162:163], v[2:3], v[108:109] op_sel:[0,0] op_sel_hi:[1,0]
	v_pk_fma_f32 v[160:161], v[4:5], v[82:83], v[160:161] op_sel:[0,1,0] op_sel_hi:[1,1,1]
	v_pk_fma_f32 v[162:163], v[4:5], v[108:109], v[162:163] op_sel:[0,1,0] op_sel_hi:[1,1,1]
	v_pk_fma_f32 v[160:161], v[6:7], v[84:85], v[160:161] op_sel:[0,0,0] op_sel_hi:[1,0,1]
	v_pk_fma_f32 v[162:163], v[6:7], v[110:111], v[162:163] op_sel:[0,0,0] op_sel_hi:[1,0,1]
	v_pk_fma_f32 v[160:161], v[8:9], v[84:85], v[160:161] op_sel:[0,1,0] op_sel_hi:[1,1,1]
	v_pk_fma_f32 v[162:163], v[8:9], v[110:111], v[162:163] op_sel:[0,1,0] op_sel_hi:[1,1,1]
	v_pk_fma_f32 v[160:161], v[10:11], v[86:87], v[160:161] op_sel:[0,0,0] op_sel_hi:[1,0,1]
	v_pk_fma_f32 v[162:163], v[10:11], v[112:113], v[162:163] op_sel:[0,0,0] op_sel_hi:[1,0,1]
	v_pk_fma_f32 v[160:161], v[12:13], v[86:87], v[160:161] op_sel:[0,1,0] op_sel_hi:[1,1,1]
	v_pk_fma_f32 v[162:163], v[12:13], v[112:113], v[162:163] op_sel:[0,1,0] op_sel_hi:[1,1,1]
	v_pk_fma_f32 v[160:161], v[14:15], v[88:89], v[160:161] op_sel:[0,0,0] op_sel_hi:[1,0,1]
	v_pk_fma_f32 v[162:163], v[14:15], v[114:115], v[162:163] op_sel:[0,0,0] op_sel_hi:[1,0,1]
	v_pk_fma_f32 v[160:161], v[16:17], v[88:89], v[160:161] op_sel:[0,1,0] op_sel_hi:[1,1,1]
	v_pk_fma_f32 v[162:163], v[16:17], v[114:115], v[162:163] op_sel:[0,1,0] op_sel_hi:[1,1,1]
	v_pk_mul_f32 v[136:137], v[2:3], v[74:75] op_sel:[0,0] op_sel_hi:[1,0]
	v_pk_mul_f32 v[138:139], v[4:5], v[74:75] op_sel:[0,1] op_sel_hi:[1,1]
	v_add_f32_dpp v160, v160, v160 quad_perm:[1,0,3,2] row_mask:0xf bank_mask:0xf bound_ctrl:1
	v_add_f32_dpp v161, v161, v161 quad_perm:[1,0,3,2] row_mask:0xf bank_mask:0xf bound_ctrl:1
	v_pk_mul_f32 v[140:141], v[6:7], v[76:77] op_sel:[0,0] op_sel_hi:[1,0]
	v_pk_mul_f32 v[142:143], v[8:9], v[76:77] op_sel:[0,1] op_sel_hi:[1,1]
	v_add_f32_dpp v162, v162, v162 quad_perm:[1,0,3,2] row_mask:0xf bank_mask:0xf bound_ctrl:1
	v_add_f32_dpp v163, v163, v163 quad_perm:[1,0,3,2] row_mask:0xf bank_mask:0xf bound_ctrl:1
	v_pk_mul_f32 v[148:149], v[10:11], v[78:79] op_sel:[0,0] op_sel_hi:[1,0]
	v_pk_mul_f32 v[150:151], v[12:13], v[78:79] op_sel:[0,1] op_sel_hi:[1,1]
	v_add_f32_dpp v160, v160, v160 quad_perm:[2,3,0,1] row_mask:0xf bank_mask:0xf bound_ctrl:1
	v_add_f32_dpp v161, v161, v161 quad_perm:[2,3,0,1] row_mask:0xf bank_mask:0xf bound_ctrl:1
	v_pk_mul_f32 v[152:153], v[14:15], v[80:81] op_sel:[0,0] op_sel_hi:[1,0]
	v_pk_mul_f32 v[154:155], v[16:17], v[80:81] op_sel:[0,1] op_sel_hi:[1,1]
	v_add_f32_dpp v162, v162, v162 quad_perm:[2,3,0,1] row_mask:0xf bank_mask:0xf bound_ctrl:1
	v_add_f32_dpp v163, v163, v163 quad_perm:[2,3,0,1] row_mask:0xf bank_mask:0xf bound_ctrl:1
	v_pk_fma_f32 v[136:137], v[100:101], v[116:117], v[136:137] op_sel:[0,0,0] op_sel_hi:[0,1,1]
	v_pk_fma_f32 v[138:139], v[100:101], v[116:117], v[138:139] op_sel:[1,0,0] op_sel_hi:[1,1,1]
	v_add_f32_dpp v160, v160, v160 row_half_mirror row_mask:0xf bank_mask:0xf bound_ctrl:1
	v_add_f32_dpp v161, v161, v161 row_half_mirror row_mask:0xf bank_mask:0xf bound_ctrl:1
	v_pk_fma_f32 v[140:141], v[102:103], v[116:117], v[140:141] op_sel:[0,0,0] op_sel_hi:[0,1,1]
	v_pk_fma_f32 v[142:143], v[102:103], v[116:117], v[142:143] op_sel:[1,0,0] op_sel_hi:[1,1,1]
	v_add_f32_dpp v162, v162, v162 row_half_mirror row_mask:0xf bank_mask:0xf bound_ctrl:1
	v_add_f32_dpp v163, v163, v163 row_half_mirror row_mask:0xf bank_mask:0xf bound_ctrl:1
	v_pk_fma_f32 v[148:149], v[104:105], v[116:117], v[148:149] op_sel:[0,0,0] op_sel_hi:[0,1,1]
	v_pk_fma_f32 v[150:151], v[104:105], v[116:117], v[150:151] op_sel:[1,0,0] op_sel_hi:[1,1,1]
	v_pk_fma_f32 v[152:153], v[106:107], v[116:117], v[152:153] op_sel:[0,0,0] op_sel_hi:[0,1,1]
	v_pk_fma_f32 v[154:155], v[106:107], v[116:117], v[154:155] op_sel:[1,0,0] op_sel_hi:[1,1,1]
	v_pk_mul_f32 v[144:145], v[116:117], v[118:119] op_sel:[0,1] op_sel_hi:[1,1]
	v_pk_fma_f32 v[2:3], v[92:93], v[160:161], v[136:137] op_sel:[0,0,0] op_sel_hi:[0,1,1] neg_lo:[0,1,0] neg_hi:[0,1,0]
	v_pk_fma_f32 v[144:145], v[160:161], v[118:119], v[144:145] op_sel_hi:[1,0,1] neg_lo:[1,0,0] neg_hi:[1,0,0]
	v_pk_fma_f32 v[4:5], v[92:93], v[160:161], v[138:139] op_sel:[1,0,0] op_sel_hi:[1,1,1] neg_lo:[0,1,0] neg_hi:[0,1,0]
	v_pk_fma_f32 v[6:7], v[94:95], v[160:161], v[140:141] op_sel:[0,0,0] op_sel_hi:[0,1,1] neg_lo:[0,1,0] neg_hi:[0,1,0]
	v_pk_add_f32 v[128:129], v[162:163], v[144:145]
	v_pk_fma_f32 v[8:9], v[94:95], v[160:161], v[142:143] op_sel:[1,0,0] op_sel_hi:[1,1,1] neg_lo:[0,1,0] neg_hi:[0,1,0]
	v_pk_fma_f32 v[10:11], v[96:97], v[160:161], v[148:149] op_sel:[0,0,0] op_sel_hi:[0,1,1] neg_lo:[0,1,0] neg_hi:[0,1,0]
	v_pk_fma_f32 v[12:13], v[96:97], v[160:161], v[150:151] op_sel:[1,0,0] op_sel_hi:[1,1,1] neg_lo:[0,1,0] neg_hi:[0,1,0]
	v_pk_fma_f32 v[14:15], v[98:99], v[160:161], v[152:153] op_sel:[0,0,0] op_sel_hi:[0,1,1] neg_lo:[0,1,0] neg_hi:[0,1,0]
	v_pk_fma_f32 v[16:17], v[98:99], v[160:161], v[154:155] op_sel:[1,0,0] op_sel_hi:[1,1,1] neg_lo:[0,1,0] neg_hi:[0,1,0]
	ds_write2_b32 v156, v128, v129 offset0:64 offset1:72
	ds_read_b128 v[74:77], v130 offset:4656
	ds_read_b128 v[78:81], v130 offset:4672
	ds_read_b128 v[82:85], v130 offset:4912
	ds_read_b128 v[86:89], v130 offset:4928
	ds_read_b128 v[92:95], v130 offset:5168
	ds_read_b128 v[96:99], v130 offset:5184
	ds_read_b128 v[100:103], v130 offset:5424
	ds_read_b128 v[104:107], v130 offset:5440
	ds_read_b128 v[108:111], v130 offset:5680
	ds_read_b128 v[112:115], v130 offset:5696
	ds_read_b32 v116, v132 offset:4656
	ds_read_b32 v117, v132 offset:4688
	ds_read_b64 v[118:119], v133 offset:6192
	s_waitcnt lgkmcnt(13)
; #define LAS __attribute__((address_space(3)))
; template <int R>
; __device__ __forceinline__ void rw_task(const Params& p, LAS unsigned char* shm, const int tid, const int s, const int d, const int h, const int half) {
;     ...
;                     const float v0 = sb[320 + row0], v1 = R == 2 ? sb[320 + row1] : 0.f; const f32x2 sc = *(const LAS f32x2*)(sb + 384); const float br = sc[0], kr = sc[1];
;                     if constexpr (R == 2) {
;                     f32x2 pa0 = s0[0] * kk[0], px0 = s0[0] * wr[0], pa1 = s1[0] * kk[0], px1 = s1[0] * wr[0];
; #pragma unroll
;                     for (int e = 1; e < 4; ++e) { pa0 += s0[e] * kk[e]; px0 += s0[e] * wr[e]; pa1 += s1[e] * kk[e]; px1 += s1[e] * wr[e]; }
;                     const float sa0 = red8(pa0[0] + pa0[1]), x0 = red8(px0[0] + px0[1]), sa1 = red8(pa1[0] + pa1[1]), x1 = red8(px1[0] + px1[1]);
;                     const float o0 = x0 - sa0 * br + v0 * kr, o1 = x1 - sa1 * br + v1 * kr;
;                     const f32x2 nsa0 = (f32x2){-sa0, -sa0}, nsa1 = (f32x2){-sa1, -sa1}, vv0 = (f32x2){v0, v0}, vv1 = (f32x2){v1, v1};
; #pragma unroll
;                     for (int e = 0; e < 4; ++e) { s0[e] = s0[e] * ww[e] + nsa0 * bb[e] + vv0 * kc[e]; s1[e] = s1[e] * ww[e] + nsa1 * bb[e] + vv1 * kc[e]; }
;                     ow0[(st * 64) & omask] = o0; ow1[(st * 64) & omask] = o1;
	v_pk_mul_f32 v[160:161], v[2:3], v[36:37] op_sel:[0,0] op_sel_hi:[1,0]
	v_pk_mul_f32 v[162:163], v[2:3], v[60:61] op_sel:[0,0] op_sel_hi:[1,0]
	v_pk_fma_f32 v[160:161], v[4:5], v[36:37], v[160:161] op_sel:[0,1,0] op_sel_hi:[1,1,1]
	v_pk_fma_f32 v[162:163], v[4:5], v[60:61], v[162:163] op_sel:[0,1,0] op_sel_hi:[1,1,1]
	v_pk_fma_f32 v[160:161], v[6:7], v[38:39], v[160:161] op_sel:[0,0,0] op_sel_hi:[1,0,1]
	v_pk_fma_f32 v[162:163], v[6:7], v[62:63], v[162:163] op_sel:[0,0,0] op_sel_hi:[1,0,1]
	v_pk_fma_f32 v[160:161], v[8:9], v[38:39], v[160:161] op_sel:[0,1,0] op_sel_hi:[1,1,1]
	v_pk_fma_f32 v[162:163], v[8:9], v[62:63], v[162:163] op_sel:[0,1,0] op_sel_hi:[1,1,1]
	v_pk_fma_f32 v[160:161], v[10:11], v[40:41], v[160:161] op_sel:[0,0,0] op_sel_hi:[1,0,1]
	v_pk_fma_f32 v[162:163], v[10:11], v[64:65], v[162:163] op_sel:[0,0,0] op_sel_hi:[1,0,1]
	v_pk_fma_f32 v[160:161], v[12:13], v[40:41], v[160:161] op_sel:[0,1,0] op_sel_hi:[1,1,1]
	v_pk_fma_f32 v[162:163], v[12:13], v[64:65], v[162:163] op_sel:[0,1,0] op_sel_hi:[1,1,1]
	v_pk_fma_f32 v[160:161], v[14:15], v[42:43], v[160:161] op_sel:[0,0,0] op_sel_hi:[1,0,1]
	v_pk_fma_f32 v[162:163], v[14:15], v[66:67], v[162:163] op_sel:[0,0,0] op_sel_hi:[1,0,1]
	v_pk_fma_f32 v[160:161], v[16:17], v[42:43], v[160:161] op_sel:[0,1,0] op_sel_hi:[1,1,1]
	v_pk_fma_f32 v[162:163], v[16:17], v[66:67], v[162:163] op_sel:[0,1,0] op_sel_hi:[1,1,1]
	v_pk_mul_f32 v[136:137], v[2:3], v[28:29] op_sel:[0,0] op_sel_hi:[1,0]
	v_pk_mul_f32 v[138:139], v[4:5], v[28:29] op_sel:[0,1] op_sel_hi:[1,1]
	v_add_f32_dpp v160, v160, v160 quad_perm:[1,0,3,2] row_mask:0xf bank_mask:0xf bound_ctrl:1
	v_add_f32_dpp v161, v161, v161 quad_perm:[1,0,3,2] row_mask:0xf bank_mask:0xf bound_ctrl:1
	v_pk_mul_f32 v[140:141], v[6:7], v[30:31] op_sel:[0,0] op_sel_hi:[1,0]
	v_pk_mul_f32 v[142:143], v[8:9], v[30:31] op_sel:[0,1] op_sel_hi:[1,1]
	v_add_f32_dpp v162, v162, v162 quad_perm:[1,0,3,2] row_mask:0xf bank_mask:0xf bound_ctrl:1
	v_add_f32_dpp v163, v163, v163 quad_perm:[1,0,3,2] row_mask:0xf bank_mask:0xf bound_ctrl:1
	v_pk_mul_f32 v[148:149], v[10:11], v[32:33] op_sel:[0,0] op_sel_hi:[1,0]
	v_pk_mul_f32 v[150:151], v[12:13], v[32:33] op_sel:[0,1] op_sel_hi:[1,1]
	v_add_f32_dpp v160, v160, v160 quad_perm:[2,3,0,1] row_mask:0xf bank_mask:0xf bound_ctrl:1
	v_add_f32_dpp v161, v161, v161 quad_perm:[2,3,0,1] row_mask:0xf bank_mask:0xf bound_ctrl:1
	v_pk_mul_f32 v[152:153], v[14:15], v[34:35] op_sel:[0,0] op_sel_hi:[1,0]
	v_pk_mul_f32 v[154:155], v[16:17], v[34:35] op_sel:[0,1] op_sel_hi:[1,1]
	v_add_f32_dpp v162, v162, v162 quad_perm:[2,3,0,1] row_mask:0xf bank_mask:0xf bound_ctrl:1
	v_add_f32_dpp v163, v163, v163 quad_perm:[2,3,0,1] row_mask:0xf bank_mask:0xf bound_ctrl:1
	v_pk_fma_f32 v[136:137], v[52:53], v[68:69], v[136:137] op_sel:[0,0,0] op_sel_hi:[0,1,1]
	v_pk_fma_f32 v[138:139], v[52:53], v[68:69], v[138:139] op_sel:[1,0,0] op_sel_hi:[1,1,1]
	v_add_f32_dpp v160, v160, v160 row_half_mirror row_mask:0xf bank_mask:0xf bound_ctrl:1
	v_add_f32_dpp v161, v161, v161 row_half_mirror row_mask:0xf bank_mask:0xf bound_ctrl:1
	v_pk_fma_f32 v[140:141], v[54:55], v[68:69], v[140:141] op_sel:[0,0,0] op_sel_hi:[0,1,1]
	v_pk_fma_f32 v[142:143], v[54:55], v[68:69], v[142:143] op_sel:[1,0,0] op_sel_hi:[1,1,1]
	v_add_f32_dpp v162, v162, v162 row_half_mirror row_mask:0xf bank_mask:0xf bound_ctrl:1
	v_add_f32_dpp v163, v163, v163 row_half_mirror row_mask:0xf bank_mask:0xf bound_ctrl:1
	v_pk_fma_f32 v[148:149], v[56:57], v[68:69], v[148:149] op_sel:[0,0,0] op_sel_hi:[0,1,1]
	v_pk_fma_f32 v[150:151], v[56:57], v[68:69], v[150:151] op_sel:[1,0,0] op_sel_hi:[1,1,1]
	v_pk_fma_f32 v[152:153], v[58:59], v[68:69], v[152:153] op_sel:[0,0,0] op_sel_hi:[0,1,1]
	v_pk_fma_f32 v[154:155], v[58:59], v[68:69], v[154:155] op_sel:[1,0,0] op_sel_hi:[1,1,1]
	v_pk_mul_f32 v[144:145], v[68:69], v[70:71] op_sel:[0,1] op_sel_hi:[1,1]
	v_pk_fma_f32 v[2:3], v[44:45], v[160:161], v[136:137] op_sel:[0,0,0] op_sel_hi:[0,1,1] neg_lo:[0,1,0] neg_hi:[0,1,0]
	v_pk_fma_f32 v[144:145], v[160:161], v[70:71], v[144:145] op_sel_hi:[1,0,1] neg_lo:[1,0,0] neg_hi:[1,0,0]
	v_pk_fma_f32 v[4:5], v[44:45], v[160:161], v[138:139] op_sel:[1,0,0] op_sel_hi:[1,1,1] neg_lo:[0,1,0] neg_hi:[0,1,0]
	v_pk_fma_f32 v[6:7], v[46:47], v[160:161], v[140:141] op_sel:[0,0,0] op_sel_hi:[0,1,1] neg_lo:[0,1,0] neg_hi:[0,1,0]
	v_pk_add_f32 v[128:129], v[162:163], v[144:145]
	v_pk_fma_f32 v[8:9], v[46:47], v[160:161], v[142:143] op_sel:[1,0,0] op_sel_hi:[1,1,1] neg_lo:[0,1,0] neg_hi:[0,1,0]
	v_pk_fma_f32 v[10:11], v[48:49], v[160:161], v[148:149] op_sel:[0,0,0] op_sel_hi:[0,1,1] neg_lo:[0,1,0] neg_hi:[0,1,0]
	v_pk_fma_f32 v[12:13], v[48:49], v[160:161], v[150:151] op_sel:[1,0,0] op_sel_hi:[1,1,1] neg_lo:[0,1,0] neg_hi:[0,1,0]
	v_pk_fma_f32 v[14:15], v[50:51], v[160:161], v[152:153] op_sel:[0,0,0] op_sel_hi:[0,1,1] neg_lo:[0,1,0] neg_hi:[0,1,0]
	v_pk_fma_f32 v[16:17], v[50:51], v[160:161], v[154:155] op_sel:[1,0,0] op_sel_hi:[1,1,1] neg_lo:[0,1,0] neg_hi:[0,1,0]
	ds_write2_b32 v156, v128, v129 offset0:128 offset1:136
	ds_read_b128 v[28:31], v130 offset:6208
	ds_read_b128 v[32:35], v130 offset:6224
	ds_read_b128 v[36:39], v130 offset:6464
	ds_read_b128 v[40:43], v130 offset:6480
	ds_read_b128 v[44:47], v130 offset:6720
	ds_read_b128 v[48:51], v130 offset:6736
	ds_read_b128 v[52:55], v130 offset:6976
	ds_read_b128 v[56:59], v130 offset:6992
	ds_read_b128 v[60:63], v130 offset:7232
	ds_read_b128 v[64:67], v130 offset:7248
	ds_read_b32 v68, v132 offset:6208
	ds_read_b32 v69, v132 offset:6240
	ds_read_b64 v[70:71], v133 offset:7744
	s_waitcnt lgkmcnt(13)
; #define LAS __attribute__((address_space(3)))
; template <int R>
; __device__ __forceinline__ void rw_task(const Params& p, LAS unsigned char* shm, const int tid, const int s, const int d, const int h, const int half) {
;     ...
;                     const float v0 = sb[320 + row0], v1 = R == 2 ? sb[320 + row1] : 0.f; const f32x2 sc = *(const LAS f32x2*)(sb + 384); const float br = sc[0], kr = sc[1];
;                     if constexpr (R == 2) {
;                     f32x2 pa0 = s0[0] * kk[0], px0 = s0[0] * wr[0], pa1 = s1[0] * kk[0], px1 = s1[0] * wr[0];
; #pragma unroll
;                     for (int e = 1; e < 4; ++e) { pa0 += s0[e] * kk[e]; px0 += s0[e] * wr[e]; pa1 += s1[e] * kk[e]; px1 += s1[e] * wr[e]; }
;                     const float sa0 = red8(pa0[0] + pa0[1]), x0 = red8(px0[0] + px0[1]), sa1 = red8(pa1[0] + pa1[1]), x1 = red8(px1[0] + px1[1]);
;                     const float o0 = x0 - sa0 * br + v0 * kr, o1 = x1 - sa1 * br + v1 * kr;
;                     const f32x2 nsa0 = (f32x2){-sa0, -sa0}, nsa1 = (f32x2){-sa1, -sa1}, vv0 = (f32x2){v0, v0}, vv1 = (f32x2){v1, v1};
; #pragma unroll
;                     for (int e = 0; e < 4; ++e) { s0[e] = s0[e] * ww[e] + nsa0 * bb[e] + vv0 * kc[e]; s1[e] = s1[e] * ww[e] + nsa1 * bb[e] + vv1 * kc[e]; }
;                     ow0[(st * 64) & omask] = o0; ow1[(st * 64) & omask] = o1;
	v_pk_mul_f32 v[160:161], v[2:3], v[82:83] op_sel:[0,0] op_sel_hi:[1,0]
	v_pk_mul_f32 v[162:163], v[2:3], v[108:109] op_sel:[0,0] op_sel_hi:[1,0]
	v_pk_fma_f32 v[160:161], v[4:5], v[82:83], v[160:161] op_sel:[0,1,0] op_sel_hi:[1,1,1]
	v_pk_fma_f32 v[162:163], v[4:5], v[108:109], v[162:163] op_sel:[0,1,0] op_sel_hi:[1,1,1]
	v_pk_fma_f32 v[160:161], v[6:7], v[84:85], v[160:161] op_sel:[0,0,0] op_sel_hi:[1,0,1]
	v_pk_fma_f32 v[162:163], v[6:7], v[110:111], v[162:163] op_sel:[0,0,0] op_sel_hi:[1,0,1]
	v_pk_fma_f32 v[160:161], v[8:9], v[84:85], v[160:161] op_sel:[0,1,0] op_sel_hi:[1,1,1]
	v_pk_fma_f32 v[162:163], v[8:9], v[110:111], v[162:163] op_sel:[0,1,0] op_sel_hi:[1,1,1]
	v_pk_fma_f32 v[160:161], v[10:11], v[86:87], v[160:161] op_sel:[0,0,0] op_sel_hi:[1,0,1]
	v_pk_fma_f32 v[162:163], v[10:11], v[112:113], v[162:163] op_sel:[0,0,0] op_sel_hi:[1,0,1]
	v_pk_fma_f32 v[160:161], v[12:13], v[86:87], v[160:161] op_sel:[0,1,0] op_sel_hi:[1,1,1]
	v_pk_fma_f32 v[162:163], v[12:13], v[112:113], v[162:163] op_sel:[0,1,0] op_sel_hi:[1,1,1]
	v_pk_fma_f32 v[160:161], v[14:15], v[88:89], v[160:161] op_sel:[0,0,0] op_sel_hi:[1,0,1]
	v_pk_fma_f32 v[162:163], v[14:15], v[114:115], v[162:163] op_sel:[0,0,0] op_sel_hi:[1,0,1]
	v_pk_fma_f32 v[160:161], v[16:17], v[88:89], v[160:161] op_sel:[0,1,0] op_sel_hi:[1,1,1]
	v_pk_fma_f32 v[162:163], v[16:17], v[114:115], v[162:163] op_sel:[0,1,0] op_sel_hi:[1,1,1]
	v_pk_mul_f32 v[136:137], v[2:3], v[74:75] op_sel:[0,0] op_sel_hi:[1,0]
	v_pk_mul_f32 v[138:139], v[4:5], v[74:75] op_sel:[0,1] op_sel_hi:[1,1]
	v_add_f32_dpp v160, v160, v160 quad_perm:[1,0,3,2] row_mask:0xf bank_mask:0xf bound_ctrl:1
	v_add_f32_dpp v161, v161, v161 quad_perm:[1,0,3,2] row_mask:0xf bank_mask:0xf bound_ctrl:1
	v_pk_mul_f32 v[140:141], v[6:7], v[76:77] op_sel:[0,0] op_sel_hi:[1,0]
	v_pk_mul_f32 v[142:143], v[8:9], v[76:77] op_sel:[0,1] op_sel_hi:[1,1]
	v_add_f32_dpp v162, v162, v162 quad_perm:[1,0,3,2] row_mask:0xf bank_mask:0xf bound_ctrl:1
	v_add_f32_dpp v163, v163, v163 quad_perm:[1,0,3,2] row_mask:0xf bank_mask:0xf bound_ctrl:1
	v_pk_mul_f32 v[148:149], v[10:11], v[78:79] op_sel:[0,0] op_sel_hi:[1,0]
	v_pk_mul_f32 v[150:151], v[12:13], v[78:79] op_sel:[0,1] op_sel_hi:[1,1]
	v_add_f32_dpp v160, v160, v160 quad_perm:[2,3,0,1] row_mask:0xf bank_mask:0xf bound_ctrl:1
	v_add_f32_dpp v161, v161, v161 quad_perm:[2,3,0,1] row_mask:0xf bank_mask:0xf bound_ctrl:1
	v_pk_mul_f32 v[152:153], v[14:15], v[80:81] op_sel:[0,0] op_sel_hi:[1,0]
	v_pk_mul_f32 v[154:155], v[16:17], v[80:81] op_sel:[0,1] op_sel_hi:[1,1]
	v_add_f32_dpp v162, v162, v162 quad_perm:[2,3,0,1] row_mask:0xf bank_mask:0xf bound_ctrl:1
	v_add_f32_dpp v163, v163, v163 quad_perm:[2,3,0,1] row_mask:0xf bank_mask:0xf bound_ctrl:1
	v_pk_fma_f32 v[136:137], v[100:101], v[116:117], v[136:137] op_sel:[0,0,0] op_sel_hi:[0,1,1]
	v_pk_fma_f32 v[138:139], v[100:101], v[116:117], v[138:139] op_sel:[1,0,0] op_sel_hi:[1,1,1]
	v_add_f32_dpp v160, v160, v160 row_half_mirror row_mask:0xf bank_mask:0xf bound_ctrl:1
	v_add_f32_dpp v161, v161, v161 row_half_mirror row_mask:0xf bank_mask:0xf bound_ctrl:1
	v_pk_fma_f32 v[140:141], v[102:103], v[116:117], v[140:141] op_sel:[0,0,0] op_sel_hi:[0,1,1]
	v_pk_fma_f32 v[142:143], v[102:103], v[116:117], v[142:143] op_sel:[1,0,0] op_sel_hi:[1,1,1]
	v_add_f32_dpp v162, v162, v162 row_half_mirror row_mask:0xf bank_mask:0xf bound_ctrl:1
	v_add_f32_dpp v163, v163, v163 row_half_mirror row_mask:0xf bank_mask:0xf bound_ctrl:1
	v_pk_fma_f32 v[148:149], v[104:105], v[116:117], v[148:149] op_sel:[0,0,0] op_sel_hi:[0,1,1]
	v_pk_fma_f32 v[150:151], v[104:105], v[116:117], v[150:151] op_sel:[1,0,0] op_sel_hi:[1,1,1]
	v_pk_fma_f32 v[152:153], v[106:107], v[116:117], v[152:153] op_sel:[0,0,0] op_sel_hi:[0,1,1]
	v_pk_fma_f32 v[154:155], v[106:107], v[116:117], v[154:155] op_sel:[1,0,0] op_sel_hi:[1,1,1]
	v_pk_mul_f32 v[144:145], v[116:117], v[118:119] op_sel:[0,1] op_sel_hi:[1,1]
	v_pk_fma_f32 v[2:3], v[92:93], v[160:161], v[136:137] op_sel:[0,0,0] op_sel_hi:[0,1,1] neg_lo:[0,1,0] neg_hi:[0,1,0]
	v_pk_fma_f32 v[144:145], v[160:161], v[118:119], v[144:145] op_sel_hi:[1,0,1] neg_lo:[1,0,0] neg_hi:[1,0,0]
	v_pk_fma_f32 v[4:5], v[92:93], v[160:161], v[138:139] op_sel:[1,0,0] op_sel_hi:[1,1,1] neg_lo:[0,1,0] neg_hi:[0,1,0]
	v_pk_fma_f32 v[6:7], v[94:95], v[160:161], v[140:141] op_sel:[0,0,0] op_sel_hi:[0,1,1] neg_lo:[0,1,0] neg_hi:[0,1,0]
	v_pk_add_f32 v[128:129], v[162:163], v[144:145]
	v_pk_fma_f32 v[8:9], v[94:95], v[160:161], v[142:143] op_sel:[1,0,0] op_sel_hi:[1,1,1] neg_lo:[0,1,0] neg_hi:[0,1,0]
	v_pk_fma_f32 v[10:11], v[96:97], v[160:161], v[148:149] op_sel:[0,0,0] op_sel_hi:[0,1,1] neg_lo:[0,1,0] neg_hi:[0,1,0]
	v_pk_fma_f32 v[12:13], v[96:97], v[160:161], v[150:151] op_sel:[1,0,0] op_sel_hi:[1,1,1] neg_lo:[0,1,0] neg_hi:[0,1,0]
	v_pk_fma_f32 v[14:15], v[98:99], v[160:161], v[152:153] op_sel:[0,0,0] op_sel_hi:[0,1,1] neg_lo:[0,1,0] neg_hi:[0,1,0]
	v_pk_fma_f32 v[16:17], v[98:99], v[160:161], v[154:155] op_sel:[1,0,0] op_sel_hi:[1,1,1] neg_lo:[0,1,0] neg_hi:[0,1,0]
	ds_write2_b32 v156, v128, v129 offset0:192 offset1:200
	v_add_u32_e32 v156, 0x400, v156
	ds_read_b128 v[74:77], v130 offset:7760
	ds_read_b128 v[78:81], v130 offset:7776
	ds_read_b128 v[82:85], v130 offset:8016
	ds_read_b128 v[86:89], v130 offset:8032
	ds_read_b128 v[92:95], v130 offset:8272
	ds_read_b128 v[96:99], v130 offset:8288
	ds_read_b128 v[100:103], v130 offset:8528
	ds_read_b128 v[104:107], v130 offset:8544
	ds_read_b128 v[108:111], v130 offset:8784
	ds_read_b128 v[112:115], v130 offset:8800
	ds_read_b32 v116, v132 offset:7760
	ds_read_b32 v117, v132 offset:7792
	ds_read_b64 v[118:119], v133 offset:9296
	s_waitcnt lgkmcnt(13)
; #define LAS __attribute__((address_space(3)))
; template <int R>
; __device__ __forceinline__ void rw_task(const Params& p, LAS unsigned char* shm, const int tid, const int s, const int d, const int h, const int half) {
;     ...
;                     const float v0 = sb[320 + row0], v1 = R == 2 ? sb[320 + row1] : 0.f; const f32x2 sc = *(const LAS f32x2*)(sb + 384); const float br = sc[0], kr = sc[1];
;                     if constexpr (R == 2) {
;                     f32x2 pa0 = s0[0] * kk[0], px0 = s0[0] * wr[0], pa1 = s1[0] * kk[0], px1 = s1[0] * wr[0];
; #pragma unroll
;                     for (int e = 1; e < 4; ++e) { pa0 += s0[e] * kk[e]; px0 += s0[e] * wr[e]; pa1 += s1[e] * kk[e]; px1 += s1[e] * wr[e]; }
;                     const float sa0 = red8(pa0[0] + pa0[1]), x0 = red8(px0[0] + px0[1]), sa1 = red8(pa1[0] + pa1[1]), x1 = red8(px1[0] + px1[1]);
;                     const float o0 = x0 - sa0 * br + v0 * kr, o1 = x1 - sa1 * br + v1 * kr;
;                     const f32x2 nsa0 = (f32x2){-sa0, -sa0}, nsa1 = (f32x2){-sa1, -sa1}, vv0 = (f32x2){v0, v0}, vv1 = (f32x2){v1, v1};
; #pragma unroll
;                     for (int e = 0; e < 4; ++e) { s0[e] = s0[e] * ww[e] + nsa0 * bb[e] + vv0 * kc[e]; s1[e] = s1[e] * ww[e] + nsa1 * bb[e] + vv1 * kc[e]; }
;                     ow0[(st * 64) & omask] = o0; ow1[(st * 64) & omask] = o1;
	v_pk_mul_f32 v[160:161], v[2:3], v[36:37] op_sel:[0,0] op_sel_hi:[1,0]
	v_pk_mul_f32 v[162:163], v[2:3], v[60:61] op_sel:[0,0] op_sel_hi:[1,0]
	v_pk_fma_f32 v[160:161], v[4:5], v[36:37], v[160:161] op_sel:[0,1,0] op_sel_hi:[1,1,1]
	v_pk_fma_f32 v[162:163], v[4:5], v[60:61], v[162:163] op_sel:[0,1,0] op_sel_hi:[1,1,1]
	v_pk_fma_f32 v[160:161], v[6:7], v[38:39], v[160:161] op_sel:[0,0,0] op_sel_hi:[1,0,1]
	v_pk_fma_f32 v[162:163], v[6:7], v[62:63], v[162:163] op_sel:[0,0,0] op_sel_hi:[1,0,1]
	v_pk_fma_f32 v[160:161], v[8:9], v[38:39], v[160:161] op_sel:[0,1,0] op_sel_hi:[1,1,1]
	v_pk_fma_f32 v[162:163], v[8:9], v[62:63], v[162:163] op_sel:[0,1,0] op_sel_hi:[1,1,1]
	v_pk_fma_f32 v[160:161], v[10:11], v[40:41], v[160:161] op_sel:[0,0,0] op_sel_hi:[1,0,1]
	v_pk_fma_f32 v[162:163], v[10:11], v[64:65], v[162:163] op_sel:[0,0,0] op_sel_hi:[1,0,1]
	v_pk_fma_f32 v[160:161], v[12:13], v[40:41], v[160:161] op_sel:[0,1,0] op_sel_hi:[1,1,1]
	v_pk_fma_f32 v[162:163], v[12:13], v[64:65], v[162:163] op_sel:[0,1,0] op_sel_hi:[1,1,1]
	v_pk_fma_f32 v[160:161], v[14:15], v[42:43], v[160:161] op_sel:[0,0,0] op_sel_hi:[1,0,1]
	v_pk_fma_f32 v[162:163], v[14:15], v[66:67], v[162:163] op_sel:[0,0,0] op_sel_hi:[1,0,1]
	v_pk_fma_f32 v[160:161], v[16:17], v[42:43], v[160:161] op_sel:[0,1,0] op_sel_hi:[1,1,1]
	v_pk_fma_f32 v[162:163], v[16:17], v[66:67], v[162:163] op_sel:[0,1,0] op_sel_hi:[1,1,1]
	v_pk_mul_f32 v[136:137], v[2:3], v[28:29] op_sel:[0,0] op_sel_hi:[1,0]
	v_pk_mul_f32 v[138:139], v[4:5], v[28:29] op_sel:[0,1] op_sel_hi:[1,1]
	v_add_f32_dpp v160, v160, v160 quad_perm:[1,0,3,2] row_mask:0xf bank_mask:0xf bound_ctrl:1
	v_add_f32_dpp v161, v161, v161 quad_perm:[1,0,3,2] row_mask:0xf bank_mask:0xf bound_ctrl:1
	v_pk_mul_f32 v[140:141], v[6:7], v[30:31] op_sel:[0,0] op_sel_hi:[1,0]
	v_pk_mul_f32 v[142:143], v[8:9], v[30:31] op_sel:[0,1] op_sel_hi:[1,1]
	v_add_f32_dpp v162, v162, v162 quad_perm:[1,0,3,2] row_mask:0xf bank_mask:0xf bound_ctrl:1
	v_add_f32_dpp v163, v163, v163 quad_perm:[1,0,3,2] row_mask:0xf bank_mask:0xf bound_ctrl:1
	v_pk_mul_f32 v[148:149], v[10:11], v[32:33] op_sel:[0,0] op_sel_hi:[1,0]
	v_pk_mul_f32 v[150:151], v[12:13], v[32:33] op_sel:[0,1] op_sel_hi:[1,1]
	v_add_f32_dpp v160, v160, v160 quad_perm:[2,3,0,1] row_mask:0xf bank_mask:0xf bound_ctrl:1
	v_add_f32_dpp v161, v161, v161 quad_perm:[2,3,0,1] row_mask:0xf bank_mask:0xf bound_ctrl:1
	v_pk_mul_f32 v[152:153], v[14:15], v[34:35] op_sel:[0,0] op_sel_hi:[1,0]
	v_pk_mul_f32 v[154:155], v[16:17], v[34:35] op_sel:[0,1] op_sel_hi:[1,1]
	v_add_f32_dpp v162, v162, v162 quad_perm:[2,3,0,1] row_mask:0xf bank_mask:0xf bound_ctrl:1
	v_add_f32_dpp v163, v163, v163 quad_perm:[2,3,0,1] row_mask:0xf bank_mask:0xf bound_ctrl:1
	v_pk_fma_f32 v[136:137], v[52:53], v[68:69], v[136:137] op_sel:[0,0,0] op_sel_hi:[0,1,1]
	v_pk_fma_f32 v[138:139], v[52:53], v[68:69], v[138:139] op_sel:[1,0,0] op_sel_hi:[1,1,1]
	v_add_f32_dpp v160, v160, v160 row_half_mirror row_mask:0xf bank_mask:0xf bound_ctrl:1
	v_add_f32_dpp v161, v161, v161 row_half_mirror row_mask:0xf bank_mask:0xf bound_ctrl:1
	v_pk_fma_f32 v[140:141], v[54:55], v[68:69], v[140:141] op_sel:[0,0,0] op_sel_hi:[0,1,1]
	v_pk_fma_f32 v[142:143], v[54:55], v[68:69], v[142:143] op_sel:[1,0,0] op_sel_hi:[1,1,1]
	v_add_f32_dpp v162, v162, v162 row_half_mirror row_mask:0xf bank_mask:0xf bound_ctrl:1
	v_add_f32_dpp v163, v163, v163 row_half_mirror row_mask:0xf bank_mask:0xf bound_ctrl:1
	v_pk_fma_f32 v[148:149], v[56:57], v[68:69], v[148:149] op_sel:[0,0,0] op_sel_hi:[0,1,1]
	v_pk_fma_f32 v[150:151], v[56:57], v[68:69], v[150:151] op_sel:[1,0,0] op_sel_hi:[1,1,1]
	v_pk_fma_f32 v[152:153], v[58:59], v[68:69], v[152:153] op_sel:[0,0,0] op_sel_hi:[0,1,1]
	v_pk_fma_f32 v[154:155], v[58:59], v[68:69], v[154:155] op_sel:[1,0,0] op_sel_hi:[1,1,1]
	v_pk_mul_f32 v[144:145], v[68:69], v[70:71] op_sel:[0,1] op_sel_hi:[1,1]
	v_pk_fma_f32 v[2:3], v[44:45], v[160:161], v[136:137] op_sel:[0,0,0] op_sel_hi:[0,1,1] neg_lo:[0,1,0] neg_hi:[0,1,0]
	v_pk_fma_f32 v[144:145], v[160:161], v[70:71], v[144:145] op_sel_hi:[1,0,1] neg_lo:[1,0,0] neg_hi:[1,0,0]
	v_pk_fma_f32 v[4:5], v[44:45], v[160:161], v[138:139] op_sel:[1,0,0] op_sel_hi:[1,1,1] neg_lo:[0,1,0] neg_hi:[0,1,0]
	v_pk_fma_f32 v[6:7], v[46:47], v[160:161], v[140:141] op_sel:[0,0,0] op_sel_hi:[0,1,1] neg_lo:[0,1,0] neg_hi:[0,1,0]
	v_pk_add_f32 v[128:129], v[162:163], v[144:145]
	v_pk_fma_f32 v[8:9], v[46:47], v[160:161], v[142:143] op_sel:[1,0,0] op_sel_hi:[1,1,1] neg_lo:[0,1,0] neg_hi:[0,1,0]
	v_pk_fma_f32 v[10:11], v[48:49], v[160:161], v[148:149] op_sel:[0,0,0] op_sel_hi:[0,1,1] neg_lo:[0,1,0] neg_hi:[0,1,0]
	v_pk_fma_f32 v[12:13], v[48:49], v[160:161], v[150:151] op_sel:[1,0,0] op_sel_hi:[1,1,1] neg_lo:[0,1,0] neg_hi:[0,1,0]
	v_pk_fma_f32 v[14:15], v[50:51], v[160:161], v[152:153] op_sel:[0,0,0] op_sel_hi:[0,1,1] neg_lo:[0,1,0] neg_hi:[0,1,0]
	v_pk_fma_f32 v[16:17], v[50:51], v[160:161], v[154:155] op_sel:[1,0,0] op_sel_hi:[1,1,1] neg_lo:[0,1,0] neg_hi:[0,1,0]
	ds_write2_b32 v156, v128, v129 offset0:0 offset1:8
	ds_read_b128 v[28:31], v130 offset:9312
	ds_read_b128 v[32:35], v130 offset:9328
	ds_read_b128 v[36:39], v130 offset:9568
	ds_read_b128 v[40:43], v130 offset:9584
	ds_read_b128 v[44:47], v130 offset:9824
	ds_read_b128 v[48:51], v130 offset:9840
	ds_read_b128 v[52:55], v130 offset:10080
	ds_read_b128 v[56:59], v130 offset:10096
	ds_read_b128 v[60:63], v130 offset:10336
	ds_read_b128 v[64:67], v130 offset:10352
	ds_read_b32 v68, v132 offset:9312
	ds_read_b32 v69, v132 offset:9344
	ds_read_b64 v[70:71], v133 offset:10848
	s_waitcnt lgkmcnt(13)
; #define LAS __attribute__((address_space(3)))
; template <int R>
; __device__ __forceinline__ void rw_task(const Params& p, LAS unsigned char* shm, const int tid, const int s, const int d, const int h, const int half) {
;     ...
;                     const float v0 = sb[320 + row0], v1 = R == 2 ? sb[320 + row1] : 0.f; const f32x2 sc = *(const LAS f32x2*)(sb + 384); const float br = sc[0], kr = sc[1];
;                     if constexpr (R == 2) {
;                     f32x2 pa0 = s0[0] * kk[0], px0 = s0[0] * wr[0], pa1 = s1[0] * kk[0], px1 = s1[0] * wr[0];
; #pragma unroll
;                     for (int e = 1; e < 4; ++e) { pa0 += s0[e] * kk[e]; px0 += s0[e] * wr[e]; pa1 += s1[e] * kk[e]; px1 += s1[e] * wr[e]; }
;                     const float sa0 = red8(pa0[0] + pa0[1]), x0 = red8(px0[0] + px0[1]), sa1 = red8(pa1[0] + pa1[1]), x1 = red8(px1[0] + px1[1]);
;                     const float o0 = x0 - sa0 * br + v0 * kr, o1 = x1 - sa1 * br + v1 * kr;
;                     const f32x2 nsa0 = (f32x2){-sa0, -sa0}, nsa1 = (f32x2){-sa1, -sa1}, vv0 = (f32x2){v0, v0}, vv1 = (f32x2){v1, v1};
; #pragma unroll
;                     for (int e = 0; e < 4; ++e) { s0[e] = s0[e] * ww[e] + nsa0 * bb[e] + vv0 * kc[e]; s1[e] = s1[e] * ww[e] + nsa1 * bb[e] + vv1 * kc[e]; }
;                     ow0[(st * 64) & omask] = o0; ow1[(st * 64) & omask] = o1;
	v_pk_mul_f32 v[160:161], v[2:3], v[82:83] op_sel:[0,0] op_sel_hi:[1,0]
	v_pk_mul_f32 v[162:163], v[2:3], v[108:109] op_sel:[0,0] op_sel_hi:[1,0]
	v_pk_fma_f32 v[160:161], v[4:5], v[82:83], v[160:161] op_sel:[0,1,0] op_sel_hi:[1,1,1]
	v_pk_fma_f32 v[162:163], v[4:5], v[108:109], v[162:163] op_sel:[0,1,0] op_sel_hi:[1,1,1]
	v_pk_fma_f32 v[160:161], v[6:7], v[84:85], v[160:161] op_sel:[0,0,0] op_sel_hi:[1,0,1]
	v_pk_fma_f32 v[162:163], v[6:7], v[110:111], v[162:163] op_sel:[0,0,0] op_sel_hi:[1,0,1]
	v_pk_fma_f32 v[160:161], v[8:9], v[84:85], v[160:161] op_sel:[0,1,0] op_sel_hi:[1,1,1]
	v_pk_fma_f32 v[162:163], v[8:9], v[110:111], v[162:163] op_sel:[0,1,0] op_sel_hi:[1,1,1]
	v_pk_fma_f32 v[160:161], v[10:11], v[86:87], v[160:161] op_sel:[0,0,0] op_sel_hi:[1,0,1]
	v_pk_fma_f32 v[162:163], v[10:11], v[112:113], v[162:163] op_sel:[0,0,0] op_sel_hi:[1,0,1]
	v_pk_fma_f32 v[160:161], v[12:13], v[86:87], v[160:161] op_sel:[0,1,0] op_sel_hi:[1,1,1]
	v_pk_fma_f32 v[162:163], v[12:13], v[112:113], v[162:163] op_sel:[0,1,0] op_sel_hi:[1,1,1]
	v_pk_fma_f32 v[160:161], v[14:15], v[88:89], v[160:161] op_sel:[0,0,0] op_sel_hi:[1,0,1]
	v_pk_fma_f32 v[162:163], v[14:15], v[114:115], v[162:163] op_sel:[0,0,0] op_sel_hi:[1,0,1]
	v_pk_fma_f32 v[160:161], v[16:17], v[88:89], v[160:161] op_sel:[0,1,0] op_sel_hi:[1,1,1]
	v_pk_fma_f32 v[162:163], v[16:17], v[114:115], v[162:163] op_sel:[0,1,0] op_sel_hi:[1,1,1]
	v_pk_mul_f32 v[136:137], v[2:3], v[74:75] op_sel:[0,0] op_sel_hi:[1,0]
	v_pk_mul_f32 v[138:139], v[4:5], v[74:75] op_sel:[0,1] op_sel_hi:[1,1]
	v_add_f32_dpp v160, v160, v160 quad_perm:[1,0,3,2] row_mask:0xf bank_mask:0xf bound_ctrl:1
	v_add_f32_dpp v161, v161, v161 quad_perm:[1,0,3,2] row_mask:0xf bank_mask:0xf bound_ctrl:1
	v_pk_mul_f32 v[140:141], v[6:7], v[76:77] op_sel:[0,0] op_sel_hi:[1,0]
	v_pk_mul_f32 v[142:143], v[8:9], v[76:77] op_sel:[0,1] op_sel_hi:[1,1]
	v_add_f32_dpp v162, v162, v162 quad_perm:[1,0,3,2] row_mask:0xf bank_mask:0xf bound_ctrl:1
	v_add_f32_dpp v163, v163, v163 quad_perm:[1,0,3,2] row_mask:0xf bank_mask:0xf bound_ctrl:1
	v_pk_mul_f32 v[148:149], v[10:11], v[78:79] op_sel:[0,0] op_sel_hi:[1,0]
	v_pk_mul_f32 v[150:151], v[12:13], v[78:79] op_sel:[0,1] op_sel_hi:[1,1]
	v_add_f32_dpp v160, v160, v160 quad_perm:[2,3,0,1] row_mask:0xf bank_mask:0xf bound_ctrl:1
	v_add_f32_dpp v161, v161, v161 quad_perm:[2,3,0,1] row_mask:0xf bank_mask:0xf bound_ctrl:1
	v_pk_mul_f32 v[152:153], v[14:15], v[80:81] op_sel:[0,0] op_sel_hi:[1,0]
	v_pk_mul_f32 v[154:155], v[16:17], v[80:81] op_sel:[0,1] op_sel_hi:[1,1]
	v_add_f32_dpp v162, v162, v162 quad_perm:[2,3,0,1] row_mask:0xf bank_mask:0xf bound_ctrl:1
	v_add_f32_dpp v163, v163, v163 quad_perm:[2,3,0,1] row_mask:0xf bank_mask:0xf bound_ctrl:1
	v_pk_fma_f32 v[136:137], v[100:101], v[116:117], v[136:137] op_sel:[0,0,0] op_sel_hi:[0,1,1]
	v_pk_fma_f32 v[138:139], v[100:101], v[116:117], v[138:139] op_sel:[1,0,0] op_sel_hi:[1,1,1]
	v_add_f32_dpp v160, v160, v160 row_half_mirror row_mask:0xf bank_mask:0xf bound_ctrl:1
	v_add_f32_dpp v161, v161, v161 row_half_mirror row_mask:0xf bank_mask:0xf bound_ctrl:1
	v_pk_fma_f32 v[140:141], v[102:103], v[116:117], v[140:141] op_sel:[0,0,0] op_sel_hi:[0,1,1]
	v_pk_fma_f32 v[142:143], v[102:103], v[116:117], v[142:143] op_sel:[1,0,0] op_sel_hi:[1,1,1]
	v_add_f32_dpp v162, v162, v162 row_half_mirror row_mask:0xf bank_mask:0xf bound_ctrl:1
	v_add_f32_dpp v163, v163, v163 row_half_mirror row_mask:0xf bank_mask:0xf bound_ctrl:1
	v_pk_fma_f32 v[148:149], v[104:105], v[116:117], v[148:149] op_sel:[0,0,0] op_sel_hi:[0,1,1]
	v_pk_fma_f32 v[150:151], v[104:105], v[116:117], v[150:151] op_sel:[1,0,0] op_sel_hi:[1,1,1]
	v_pk_fma_f32 v[152:153], v[106:107], v[116:117], v[152:153] op_sel:[0,0,0] op_sel_hi:[0,1,1]
	v_pk_fma_f32 v[154:155], v[106:107], v[116:117], v[154:155] op_sel:[1,0,0] op_sel_hi:[1,1,1]
	v_pk_mul_f32 v[144:145], v[116:117], v[118:119] op_sel:[0,1] op_sel_hi:[1,1]
	v_pk_fma_f32 v[2:3], v[92:93], v[160:161], v[136:137] op_sel:[0,0,0] op_sel_hi:[0,1,1] neg_lo:[0,1,0] neg_hi:[0,1,0]
	v_pk_fma_f32 v[144:145], v[160:161], v[118:119], v[144:145] op_sel_hi:[1,0,1] neg_lo:[1,0,0] neg_hi:[1,0,0]
	v_pk_fma_f32 v[4:5], v[92:93], v[160:161], v[138:139] op_sel:[1,0,0] op_sel_hi:[1,1,1] neg_lo:[0,1,0] neg_hi:[0,1,0]
	v_pk_fma_f32 v[6:7], v[94:95], v[160:161], v[140:141] op_sel:[0,0,0] op_sel_hi:[0,1,1] neg_lo:[0,1,0] neg_hi:[0,1,0]
	v_pk_add_f32 v[128:129], v[162:163], v[144:145]
	v_pk_fma_f32 v[8:9], v[94:95], v[160:161], v[142:143] op_sel:[1,0,0] op_sel_hi:[1,1,1] neg_lo:[0,1,0] neg_hi:[0,1,0]
	v_pk_fma_f32 v[10:11], v[96:97], v[160:161], v[148:149] op_sel:[0,0,0] op_sel_hi:[0,1,1] neg_lo:[0,1,0] neg_hi:[0,1,0]
	v_pk_fma_f32 v[12:13], v[96:97], v[160:161], v[150:151] op_sel:[1,0,0] op_sel_hi:[1,1,1] neg_lo:[0,1,0] neg_hi:[0,1,0]
	v_pk_fma_f32 v[14:15], v[98:99], v[160:161], v[152:153] op_sel:[0,0,0] op_sel_hi:[0,1,1] neg_lo:[0,1,0] neg_hi:[0,1,0]
	v_pk_fma_f32 v[16:17], v[98:99], v[160:161], v[154:155] op_sel:[1,0,0] op_sel_hi:[1,1,1] neg_lo:[0,1,0] neg_hi:[0,1,0]
	ds_write2_b32 v156, v128, v129 offset0:64 offset1:72
	ds_read_b128 v[74:77], v130 offset:10864
	ds_read_b128 v[78:81], v130 offset:10880
	ds_read_b128 v[82:85], v130 offset:11120
	ds_read_b128 v[86:89], v130 offset:11136
	ds_read_b128 v[92:95], v130 offset:11376
	ds_read_b128 v[96:99], v130 offset:11392
	ds_read_b128 v[100:103], v130 offset:11632
	ds_read_b128 v[104:107], v130 offset:11648
	ds_read_b128 v[108:111], v130 offset:11888
	ds_read_b128 v[112:115], v130 offset:11904
	ds_read_b32 v116, v132 offset:10864
	ds_read_b32 v117, v132 offset:10896
	ds_read_b64 v[118:119], v133 offset:12400
	s_waitcnt lgkmcnt(13)
; #define LAS __attribute__((address_space(3)))
; template <int R>
; __device__ __forceinline__ void rw_task(const Params& p, LAS unsigned char* shm, const int tid, const int s, const int d, const int h, const int half) {
;     ...
;                     const float v0 = sb[320 + row0], v1 = R == 2 ? sb[320 + row1] : 0.f; const f32x2 sc = *(const LAS f32x2*)(sb + 384); const float br = sc[0], kr = sc[1];
;                     if constexpr (R == 2) {
;                     f32x2 pa0 = s0[0] * kk[0], px0 = s0[0] * wr[0], pa1 = s1[0] * kk[0], px1 = s1[0] * wr[0];
; #pragma unroll
;                     for (int e = 1; e < 4; ++e) { pa0 += s0[e] * kk[e]; px0 += s0[e] * wr[e]; pa1 += s1[e] * kk[e]; px1 += s1[e] * wr[e]; }
;                     const float sa0 = red8(pa0[0] + pa0[1]), x0 = red8(px0[0] + px0[1]), sa1 = red8(pa1[0] + pa1[1]), x1 = red8(px1[0] + px1[1]);
;                     const float o0 = x0 - sa0 * br + v0 * kr, o1 = x1 - sa1 * br + v1 * kr;
;                     const f32x2 nsa0 = (f32x2){-sa0, -sa0}, nsa1 = (f32x2){-sa1, -sa1}, vv0 = (f32x2){v0, v0}, vv1 = (f32x2){v1, v1};
; #pragma unroll
;                     for (int e = 0; e < 4; ++e) { s0[e] = s0[e] * ww[e] + nsa0 * bb[e] + vv0 * kc[e]; s1[e] = s1[e] * ww[e] + nsa1 * bb[e] + vv1 * kc[e]; }
;                     ow0[(st * 64) & omask] = o0; ow1[(st * 64) & omask] = o1;
	v_pk_mul_f32 v[160:161], v[2:3], v[36:37] op_sel:[0,0] op_sel_hi:[1,0]
	v_pk_mul_f32 v[162:163], v[2:3], v[60:61] op_sel:[0,0] op_sel_hi:[1,0]
	v_pk_fma_f32 v[160:161], v[4:5], v[36:37], v[160:161] op_sel:[0,1,0] op_sel_hi:[1,1,1]
	v_pk_fma_f32 v[162:163], v[4:5], v[60:61], v[162:163] op_sel:[0,1,0] op_sel_hi:[1,1,1]
	v_pk_fma_f32 v[160:161], v[6:7], v[38:39], v[160:161] op_sel:[0,0,0] op_sel_hi:[1,0,1]
	v_pk_fma_f32 v[162:163], v[6:7], v[62:63], v[162:163] op_sel:[0,0,0] op_sel_hi:[1,0,1]
	v_pk_fma_f32 v[160:161], v[8:9], v[38:39], v[160:161] op_sel:[0,1,0] op_sel_hi:[1,1,1]
	v_pk_fma_f32 v[162:163], v[8:9], v[62:63], v[162:163] op_sel:[0,1,0] op_sel_hi:[1,1,1]
	v_pk_fma_f32 v[160:161], v[10:11], v[40:41], v[160:161] op_sel:[0,0,0] op_sel_hi:[1,0,1]
	v_pk_fma_f32 v[162:163], v[10:11], v[64:65], v[162:163] op_sel:[0,0,0] op_sel_hi:[1,0,1]
	v_pk_fma_f32 v[160:161], v[12:13], v[40:41], v[160:161] op_sel:[0,1,0] op_sel_hi:[1,1,1]
	v_pk_fma_f32 v[162:163], v[12:13], v[64:65], v[162:163] op_sel:[0,1,0] op_sel_hi:[1,1,1]
	v_pk_fma_f32 v[160:161], v[14:15], v[42:43], v[160:161] op_sel:[0,0,0] op_sel_hi:[1,0,1]
	v_pk_fma_f32 v[162:163], v[14:15], v[66:67], v[162:163] op_sel:[0,0,0] op_sel_hi:[1,0,1]
	v_pk_fma_f32 v[160:161], v[16:17], v[42:43], v[160:161] op_sel:[0,1,0] op_sel_hi:[1,1,1]
	v_pk_fma_f32 v[162:163], v[16:17], v[66:67], v[162:163] op_sel:[0,1,0] op_sel_hi:[1,1,1]
	v_pk_mul_f32 v[136:137], v[2:3], v[28:29] op_sel:[0,0] op_sel_hi:[1,0]
	v_pk_mul_f32 v[138:139], v[4:5], v[28:29] op_sel:[0,1] op_sel_hi:[1,1]
	v_add_f32_dpp v160, v160, v160 quad_perm:[1,0,3,2] row_mask:0xf bank_mask:0xf bound_ctrl:1
	v_add_f32_dpp v161, v161, v161 quad_perm:[1,0,3,2] row_mask:0xf bank_mask:0xf bound_ctrl:1
	v_pk_mul_f32 v[140:141], v[6:7], v[30:31] op_sel:[0,0] op_sel_hi:[1,0]
	v_pk_mul_f32 v[142:143], v[8:9], v[30:31] op_sel:[0,1] op_sel_hi:[1,1]
	v_add_f32_dpp v162, v162, v162 quad_perm:[1,0,3,2] row_mask:0xf bank_mask:0xf bound_ctrl:1
	v_add_f32_dpp v163, v163, v163 quad_perm:[1,0,3,2] row_mask:0xf bank_mask:0xf bound_ctrl:1
	v_pk_mul_f32 v[148:149], v[10:11], v[32:33] op_sel:[0,0] op_sel_hi:[1,0]
	v_pk_mul_f32 v[150:151], v[12:13], v[32:33] op_sel:[0,1] op_sel_hi:[1,1]
	v_add_f32_dpp v160, v160, v160 quad_perm:[2,3,0,1] row_mask:0xf bank_mask:0xf bound_ctrl:1
	v_add_f32_dpp v161, v161, v161 quad_perm:[2,3,0,1] row_mask:0xf bank_mask:0xf bound_ctrl:1
	v_pk_mul_f32 v[152:153], v[14:15], v[34:35] op_sel:[0,0] op_sel_hi:[1,0]
	v_pk_mul_f32 v[154:155], v[16:17], v[34:35] op_sel:[0,1] op_sel_hi:[1,1]
	v_add_f32_dpp v162, v162, v162 quad_perm:[2,3,0,1] row_mask:0xf bank_mask:0xf bound_ctrl:1
	v_add_f32_dpp v163, v163, v163 quad_perm:[2,3,0,1] row_mask:0xf bank_mask:0xf bound_ctrl:1
	v_pk_fma_f32 v[136:137], v[52:53], v[68:69], v[136:137] op_sel:[0,0,0] op_sel_hi:[0,1,1]
	v_pk_fma_f32 v[138:139], v[52:53], v[68:69], v[138:139] op_sel:[1,0,0] op_sel_hi:[1,1,1]
	v_add_f32_dpp v160, v160, v160 row_half_mirror row_mask:0xf bank_mask:0xf bound_ctrl:1
	v_add_f32_dpp v161, v161, v161 row_half_mirror row_mask:0xf bank_mask:0xf bound_ctrl:1
	v_pk_fma_f32 v[140:141], v[54:55], v[68:69], v[140:141] op_sel:[0,0,0] op_sel_hi:[0,1,1]
	v_pk_fma_f32 v[142:143], v[54:55], v[68:69], v[142:143] op_sel:[1,0,0] op_sel_hi:[1,1,1]
	v_add_f32_dpp v162, v162, v162 row_half_mirror row_mask:0xf bank_mask:0xf bound_ctrl:1
	v_add_f32_dpp v163, v163, v163 row_half_mirror row_mask:0xf bank_mask:0xf bound_ctrl:1
	v_pk_fma_f32 v[148:149], v[56:57], v[68:69], v[148:149] op_sel:[0,0,0] op_sel_hi:[0,1,1]
	v_pk_fma_f32 v[150:151], v[56:57], v[68:69], v[150:151] op_sel:[1,0,0] op_sel_hi:[1,1,1]
	v_pk_fma_f32 v[152:153], v[58:59], v[68:69], v[152:153] op_sel:[0,0,0] op_sel_hi:[0,1,1]
	v_pk_fma_f32 v[154:155], v[58:59], v[68:69], v[154:155] op_sel:[1,0,0] op_sel_hi:[1,1,1]
	v_pk_mul_f32 v[144:145], v[68:69], v[70:71] op_sel:[0,1] op_sel_hi:[1,1]
	v_pk_fma_f32 v[2:3], v[44:45], v[160:161], v[136:137] op_sel:[0,0,0] op_sel_hi:[0,1,1] neg_lo:[0,1,0] neg_hi:[0,1,0]
	v_pk_fma_f32 v[144:145], v[160:161], v[70:71], v[144:145] op_sel_hi:[1,0,1] neg_lo:[1,0,0] neg_hi:[1,0,0]
	v_pk_fma_f32 v[4:5], v[44:45], v[160:161], v[138:139] op_sel:[1,0,0] op_sel_hi:[1,1,1] neg_lo:[0,1,0] neg_hi:[0,1,0]
	v_pk_fma_f32 v[6:7], v[46:47], v[160:161], v[140:141] op_sel:[0,0,0] op_sel_hi:[0,1,1] neg_lo:[0,1,0] neg_hi:[0,1,0]
	v_pk_add_f32 v[128:129], v[162:163], v[144:145]
	v_pk_fma_f32 v[8:9], v[46:47], v[160:161], v[142:143] op_sel:[1,0,0] op_sel_hi:[1,1,1] neg_lo:[0,1,0] neg_hi:[0,1,0]
	v_pk_fma_f32 v[10:11], v[48:49], v[160:161], v[148:149] op_sel:[0,0,0] op_sel_hi:[0,1,1] neg_lo:[0,1,0] neg_hi:[0,1,0]
	v_pk_fma_f32 v[12:13], v[48:49], v[160:161], v[150:151] op_sel:[1,0,0] op_sel_hi:[1,1,1] neg_lo:[0,1,0] neg_hi:[0,1,0]
	v_pk_fma_f32 v[14:15], v[50:51], v[160:161], v[152:153] op_sel:[0,0,0] op_sel_hi:[0,1,1] neg_lo:[0,1,0] neg_hi:[0,1,0]
	v_pk_fma_f32 v[16:17], v[50:51], v[160:161], v[154:155] op_sel:[1,0,0] op_sel_hi:[1,1,1] neg_lo:[0,1,0] neg_hi:[0,1,0]
	ds_write2_b32 v156, v128, v129 offset0:128 offset1:136
	ds_read_b128 v[28:31], v130 offset:12416
	ds_read_b128 v[32:35], v130 offset:12432
	ds_read_b128 v[36:39], v130 offset:12672
	ds_read_b128 v[40:43], v130 offset:12688
	ds_read_b128 v[44:47], v130 offset:12928
	ds_read_b128 v[48:51], v130 offset:12944
	ds_read_b128 v[52:55], v130 offset:13184
	ds_read_b128 v[56:59], v130 offset:13200
	ds_read_b128 v[60:63], v130 offset:13440
	ds_read_b128 v[64:67], v130 offset:13456
	ds_read_b32 v68, v132 offset:12416
	ds_read_b32 v69, v132 offset:12448
	ds_read_b64 v[70:71], v133 offset:13952
	s_waitcnt lgkmcnt(13)
; #define LAS __attribute__((address_space(3)))
; template <int R>
; __device__ __forceinline__ void rw_task(const Params& p, LAS unsigned char* shm, const int tid, const int s, const int d, const int h, const int half) {
;     ...
;                 for (int st = 0; st < TT; ++st) {
;                     const LAS float* sb = ib + st * RW_STRIDE;
;                     f32x2 ww[4], kk[4], bb[4], kc[4], wr[4];
;                     { const f32x4 a = *(const LAS f32x4*)(sb + 8 * j), b = *(const LAS f32x4*)(sb + 8 * j + 4); ww[0] = (f32x2){a[0], a[1]}; ww[1] = (f32x2){a[2], a[3]}; ww[2] = (f32x2){b[0], b[1]}; ww[3] = (f32x2){b[2], b[3]}; }
;                     { const f32x4 a = *(const LAS f32x4*)(sb + 64 + 8 * j), b = *(const LAS f32x4*)(sb + 64 + 8 * j + 4); kk[0] = (f32x2){a[0], a[1]}; kk[1] = (f32x2){a[2], a[3]}; kk[2] = (f32x2){b[0], b[1]}; kk[3] = (f32x2){b[2], b[3]}; }
;                     { const f32x4 a = *(const LAS f32x4*)(sb + 128 + 8 * j), b = *(const LAS f32x4*)(sb + 128 + 8 * j + 4); bb[0] = (f32x2){a[0], a[1]}; bb[1] = (f32x2){a[2], a[3]}; bb[2] = (f32x2){b[0], b[1]}; bb[3] = (f32x2){b[2], b[3]}; }
;                     { const f32x4 a = *(const LAS f32x4*)(sb + 192 + 8 * j), b = *(const LAS f32x4*)(sb + 192 + 8 * j + 4); kc[0] = (f32x2){a[0], a[1]}; kc[1] = (f32x2){a[2], a[3]}; kc[2] = (f32x2){b[0], b[1]}; kc[3] = (f32x2){b[2], b[3]}; }
;                     { const f32x4 a = *(const LAS f32x4*)(sb + 256 + 8 * j), b = *(const LAS f32x4*)(sb + 256 + 8 * j + 4); wr[0] = (f32x2){a[0], a[1]}; wr[1] = (f32x2){a[2], a[3]}; wr[2] = (f32x2){b[0], b[1]}; wr[3] = (f32x2){b[2], b[3]}; }
;                     const float v0 = sb[320 + row0], v1 = R == 2 ? sb[320 + row1] : 0.f; const f32x2 sc = *(const LAS f32x2*)(sb + 384); const float br = sc[0], kr = sc[1];
;                     if constexpr (R == 2) {
;                     f32x2 pa0 = s0[0] * kk[0], px0 = s0[0] * wr[0], pa1 = s1[0] * kk[0], px1 = s1[0] * wr[0];
; #pragma unroll
;                     for (int e = 1; e < 4; ++e) { pa0 += s0[e] * kk[e]; px0 += s0[e] * wr[e]; pa1 += s1[e] * kk[e]; px1 += s1[e] * wr[e]; }
;                     const float sa0 = red8(pa0[0] + pa0[1]), x0 = red8(px0[0] + px0[1]), sa1 = red8(pa1[0] + pa1[1]), x1 = red8(px1[0] + px1[1]);
;                     const float o0 = x0 - sa0 * br + v0 * kr, o1 = x1 - sa1 * br + v1 * kr;
	v_pk_mul_f32 v[160:161], v[2:3], v[82:83] op_sel:[0,0] op_sel_hi:[1,0]
	v_pk_mul_f32 v[162:163], v[2:3], v[108:109] op_sel:[0,0] op_sel_hi:[1,0]
	v_pk_fma_f32 v[160:161], v[4:5], v[82:83], v[160:161] op_sel:[0,1,0] op_sel_hi:[1,1,1]
	v_pk_fma_f32 v[162:163], v[4:5], v[108:109], v[162:163] op_sel:[0,1,0] op_sel_hi:[1,1,1]
	v_pk_fma_f32 v[160:161], v[6:7], v[84:85], v[160:161] op_sel:[0,0,0] op_sel_hi:[1,0,1]
	v_pk_fma_f32 v[162:163], v[6:7], v[110:111], v[162:163] op_sel:[0,0,0] op_sel_hi:[1,0,1]
	v_pk_fma_f32 v[160:161], v[8:9], v[84:85], v[160:161] op_sel:[0,1,0] op_sel_hi:[1,1,1]
	v_pk_fma_f32 v[162:163], v[8:9], v[110:111], v[162:163] op_sel:[0,1,0] op_sel_hi:[1,1,1]
	v_pk_fma_f32 v[160:161], v[10:11], v[86:87], v[160:161] op_sel:[0,0,0] op_sel_hi:[1,0,1]
	v_pk_fma_f32 v[162:163], v[10:11], v[112:113], v[162:163] op_sel:[0,0,0] op_sel_hi:[1,0,1]
	v_pk_fma_f32 v[160:161], v[12:13], v[86:87], v[160:161] op_sel:[0,1,0] op_sel_hi:[1,1,1]
	v_pk_fma_f32 v[162:163], v[12:13], v[112:113], v[162:163] op_sel:[0,1,0] op_sel_hi:[1,1,1]
	v_pk_fma_f32 v[160:161], v[14:15], v[88:89], v[160:161] op_sel:[0,0,0] op_sel_hi:[1,0,1]
	v_pk_fma_f32 v[162:163], v[14:15], v[114:115], v[162:163] op_sel:[0,0,0] op_sel_hi:[1,0,1]
	v_pk_fma_f32 v[160:161], v[16:17], v[88:89], v[160:161] op_sel:[0,1,0] op_sel_hi:[1,1,1]
	v_pk_fma_f32 v[162:163], v[16:17], v[114:115], v[162:163] op_sel:[0,1,0] op_sel_hi:[1,1,1]
	v_pk_mul_f32 v[136:137], v[2:3], v[74:75] op_sel:[0,0] op_sel_hi:[1,0]
	v_pk_mul_f32 v[138:139], v[4:5], v[74:75] op_sel:[0,1] op_sel_hi:[1,1]
	v_add_f32_dpp v160, v160, v160 quad_perm:[1,0,3,2] row_mask:0xf bank_mask:0xf bound_ctrl:1
	v_add_f32_dpp v161, v161, v161 quad_perm:[1,0,3,2] row_mask:0xf bank_mask:0xf bound_ctrl:1
	v_pk_mul_f32 v[140:141], v[6:7], v[76:77] op_sel:[0,0] op_sel_hi:[1,0]
	v_pk_mul_f32 v[142:143], v[8:9], v[76:77] op_sel:[0,1] op_sel_hi:[1,1]
	v_add_f32_dpp v162, v162, v162 quad_perm:[1,0,3,2] row_mask:0xf bank_mask:0xf bound_ctrl:1
	v_add_f32_dpp v163, v163, v163 quad_perm:[1,0,3,2] row_mask:0xf bank_mask:0xf bound_ctrl:1
	v_pk_mul_f32 v[148:149], v[10:11], v[78:79] op_sel:[0,0] op_sel_hi:[1,0]
	v_pk_mul_f32 v[150:151], v[12:13], v[78:79] op_sel:[0,1] op_sel_hi:[1,1]
	v_add_f32_dpp v160, v160, v160 quad_perm:[2,3,0,1] row_mask:0xf bank_mask:0xf bound_ctrl:1
	v_add_f32_dpp v161, v161, v161 quad_perm:[2,3,0,1] row_mask:0xf bank_mask:0xf bound_ctrl:1
	v_pk_mul_f32 v[152:153], v[14:15], v[80:81] op_sel:[0,0] op_sel_hi:[1,0]
	v_pk_mul_f32 v[154:155], v[16:17], v[80:81] op_sel:[0,1] op_sel_hi:[1,1]
	v_add_f32_dpp v162, v162, v162 quad_perm:[2,3,0,1] row_mask:0xf bank_mask:0xf bound_ctrl:1
	v_add_f32_dpp v163, v163, v163 quad_perm:[2,3,0,1] row_mask:0xf bank_mask:0xf bound_ctrl:1
	v_pk_fma_f32 v[136:137], v[100:101], v[116:117], v[136:137] op_sel:[0,0,0] op_sel_hi:[0,1,1]
	v_pk_fma_f32 v[138:139], v[100:101], v[116:117], v[138:139] op_sel:[1,0,0] op_sel_hi:[1,1,1]
	v_add_f32_dpp v160, v160, v160 row_half_mirror row_mask:0xf bank_mask:0xf bound_ctrl:1
	v_add_f32_dpp v161, v161, v161 row_half_mirror row_mask:0xf bank_mask:0xf bound_ctrl:1
	v_pk_fma_f32 v[140:141], v[102:103], v[116:117], v[140:141] op_sel:[0,0,0] op_sel_hi:[0,1,1]
	v_pk_fma_f32 v[142:143], v[102:103], v[116:117], v[142:143] op_sel:[1,0,0] op_sel_hi:[1,1,1]
	v_add_f32_dpp v162, v162, v162 row_half_mirror row_mask:0xf bank_mask:0xf bound_ctrl:1
	v_add_f32_dpp v163, v163, v163 row_half_mirror row_mask:0xf bank_mask:0xf bound_ctrl:1
	v_pk_fma_f32 v[148:149], v[104:105], v[116:117], v[148:149] op_sel:[0,0,0] op_sel_hi:[0,1,1]
	v_pk_fma_f32 v[150:151], v[104:105], v[116:117], v[150:151] op_sel:[1,0,0] op_sel_hi:[1,1,1]
	v_pk_fma_f32 v[152:153], v[106:107], v[116:117], v[152:153] op_sel:[0,0,0] op_sel_hi:[0,1,1]
	v_pk_fma_f32 v[154:155], v[106:107], v[116:117], v[154:155] op_sel:[1,0,0] op_sel_hi:[1,1,1]
	v_pk_mul_f32 v[144:145], v[116:117], v[118:119] op_sel:[0,1] op_sel_hi:[1,1]
	v_pk_fma_f32 v[2:3], v[92:93], v[160:161], v[136:137] op_sel:[0,0,0] op_sel_hi:[0,1,1] neg_lo:[0,1,0] neg_hi:[0,1,0]
	v_pk_fma_f32 v[144:145], v[160:161], v[118:119], v[144:145] op_sel_hi:[1,0,1] neg_lo:[1,0,0] neg_hi:[1,0,0]
	v_pk_fma_f32 v[4:5], v[92:93], v[160:161], v[138:139] op_sel:[1,0,0] op_sel_hi:[1,1,1] neg_lo:[0,1,0] neg_hi:[0,1,0]
	v_pk_fma_f32 v[6:7], v[94:95], v[160:161], v[140:141] op_sel:[0,0,0] op_sel_hi:[0,1,1] neg_lo:[0,1,0] neg_hi:[0,1,0]
	v_pk_add_f32 v[128:129], v[162:163], v[144:145]
	v_pk_fma_f32 v[8:9], v[94:95], v[160:161], v[142:143] op_sel:[1,0,0] op_sel_hi:[1,1,1] neg_lo:[0,1,0] neg_hi:[0,1,0]
	v_pk_fma_f32 v[10:11], v[96:97], v[160:161], v[148:149] op_sel:[0,0,0] op_sel_hi:[0,1,1] neg_lo:[0,1,0] neg_hi:[0,1,0]
	v_pk_fma_f32 v[12:13], v[96:97], v[160:161], v[150:151] op_sel:[1,0,0] op_sel_hi:[1,1,1] neg_lo:[0,1,0] neg_hi:[0,1,0]
	v_pk_fma_f32 v[14:15], v[98:99], v[160:161], v[152:153] op_sel:[0,0,0] op_sel_hi:[0,1,1] neg_lo:[0,1,0] neg_hi:[0,1,0]
	v_pk_fma_f32 v[16:17], v[98:99], v[160:161], v[154:155] op_sel:[1,0,0] op_sel_hi:[1,1,1] neg_lo:[0,1,0] neg_hi:[0,1,0]
	ds_write2_b32 v156, v128, v129 offset0:192 offset1:200
	v_add_u32_e32 v156, 0x400, v156
	v_add_u32_e32 v130, 0x3080, v130
	v_add_u32_e32 v132, 0x3080, v132
	v_add_u32_e32 v133, 0x3080, v133
	s_add_i32 s6, s6, 1
	s_cmp_eq_u32 s6, 4
	s_cbranch_scc0 .Lrw2_step
	s_add_i32 s4, s4, 1
	s_xor_b64 s[0:1], s[0:1], -1
	s_cmpk_eq_i32 s4, 0x80
	s_waitcnt lgkmcnt(0)
	s_barrier
	s_cbranch_scc0 .LBB0_205
